# v095 + P1 silu epilogue: each pk_add issued right before its two reciprocals (exp x8, then add/rcp/rcp x4) so the transcendental pipe is not held behind the last add
# baseline (speedup 1.0000x reference)
; __device__ __forceinline__ unsigned cvt_pk_bf16(float lo, float hi) { unsigned r; asm volatile("v_cvt_pk_bf16_f32 %0, %1, %2" : "=v"(r) : "v"(lo), "v"(hi)); return r; }
; __device__ __forceinline__ float silu_f(float x) { return x * __builtin_amdgcn_rcpf(1.0f + __builtin_amdgcn_exp2f(-x * LOG2E)); }
;     __device__ __forceinline__ void operator()(const f32x4 (&acc)[2][2][4][2], const pg8::Unit& u, int wr, int wc, int fr, int fq, const LAS float* tab) const {
;     ...
;         for (int ai = 0; ai < 2; ++ai)
; #pragma unroll
;             for (int m = 0; m < 4; ++m) {
;                 const int row = row0 + ai * 128 + m * 16;
;                 bf16_t* rowp = (mode == 0) ? base + (size_t)(row >> 4) * 4096 + (size_t)(wc * 512 + (row & 15) * 32 + 8 * fq) : base + (size_t)row * ldc + col0;
;                 const int bjstep = (mode == 0) ? 4 * 512 : 128;
;                 float s1 = 0.f, s2 = 0.f;
;                 const float f2 = (kind == 4) ? tab[512 + ai * 128 + wr * 64 + m * 16 + fr] : 1.0f;
; #pragma unroll
;                 for (int bj = 0; bj < 2; ++bj) {
;                     f32x4 v0 = acc[ai][bj][m][0], v1 = acc[ai][bj][m][1];
;                     if (kind == 1) {
; #pragma unroll
;                         for (int e = 0; e < 4; ++e) { v0[e] = silu_f(v0[e]); v1[e] = silu_f(v1[e]); }
;                     } else if (kind == 2) { v0 = v0 * QSCALE; v1 = v1 * QSCALE; }
;                     else if (kind == 3) {
; #pragma unroll
;                         for (int e = 0; e < 4; ++e) { s1 += v0[e] + v1[e]; s2 += v0[e] * v0[e] + v1[e] * v1[e]; }
;                     } else if (kind == 4) {
;                         v0 = v0 * f2; v1 = v1 * f2;
; #pragma unroll
;                         for (int e = 0; e < 4; ++e) s2 += v0[e] * v0[e] + v1[e] * v1[e];
;                     }
;                     u32x4 w; w.x = cvt_pk_bf16(v0[0], v0[1]); w.y = cvt_pk_bf16(v0[2], v0[3]); w.z = cvt_pk_bf16(v1[0], v1[1]); w.w = cvt_pk_bf16(v1[2], v1[3]);
;                     *(u32x4*)(rowp + bj * bjstep) = w;
.Lepi_silu:
	v_mov_b32_e32 v220, 0xbfb8aa3b
	v_mov_b32_e32 v221, 0xbfb8aa3b
	v_mov_b32_e32 v222, 1.0
	v_mov_b32_e32 v223, 1.0
	v_pk_mul_f32 v[224:225], v[126:127], v[220:221]
	v_pk_mul_f32 v[226:227], v[128:129], v[220:221]
	v_pk_mul_f32 v[228:229], v[122:123], v[220:221]
	v_pk_mul_f32 v[230:231], v[124:125], v[220:221]
	v_exp_f32_e32 v224, v224
	v_exp_f32_e32 v225, v225
	v_exp_f32_e32 v226, v226
	v_exp_f32_e32 v227, v227
	v_exp_f32_e32 v228, v228
	v_exp_f32_e32 v229, v229
	v_exp_f32_e32 v230, v230
	v_exp_f32_e32 v231, v231
	v_pk_add_f32 v[224:225], v[224:225], v[222:223]
	v_rcp_f32_e32 v224, v224
	v_rcp_f32_e32 v225, v225
	v_pk_add_f32 v[226:227], v[226:227], v[222:223]
	v_rcp_f32_e32 v226, v226
	v_rcp_f32_e32 v227, v227
	v_pk_add_f32 v[228:229], v[228:229], v[222:223]
	v_rcp_f32_e32 v228, v228
	v_rcp_f32_e32 v229, v229
	v_pk_add_f32 v[230:231], v[230:231], v[222:223]
	v_rcp_f32_e32 v230, v230
	v_rcp_f32_e32 v231, v231
	v_pk_mul_f32 v[126:127], v[126:127], v[224:225]
	v_pk_mul_f32 v[128:129], v[128:129], v[226:227]
	v_pk_mul_f32 v[122:123], v[122:123], v[228:229]
	v_pk_mul_f32 v[124:125], v[124:125], v[230:231]
	v_cvt_pk_bf16_f32 v232, v126, v127
	v_cvt_pk_bf16_f32 v233, v128, v129
	v_cvt_pk_bf16_f32 v234, v122, v123
	v_cvt_pk_bf16_f32 v235, v124, v125
	global_store_dwordx4 v252, v[232:235], s[96:97]
	s_add_u32 s96, s96, 0x1000
	s_addc_u32 s97, s97, 0
	v_pk_mul_f32 v[224:225], v[118:119], v[220:221]
	v_pk_mul_f32 v[226:227], v[120:121], v[220:221]
	v_pk_mul_f32 v[228:229], v[114:115], v[220:221]
	v_pk_mul_f32 v[230:231], v[116:117], v[220:221]
	v_exp_f32_e32 v224, v224
	v_exp_f32_e32 v225, v225
	v_exp_f32_e32 v226, v226
	v_exp_f32_e32 v227, v227
	v_exp_f32_e32 v228, v228
	v_exp_f32_e32 v229, v229
	v_exp_f32_e32 v230, v230
	v_exp_f32_e32 v231, v231
	v_pk_add_f32 v[224:225], v[224:225], v[222:223]
	v_rcp_f32_e32 v224, v224
	v_rcp_f32_e32 v225, v225
	v_pk_add_f32 v[226:227], v[226:227], v[222:223]
	v_rcp_f32_e32 v226, v226
	v_rcp_f32_e32 v227, v227
	v_pk_add_f32 v[228:229], v[228:229], v[222:223]
	v_rcp_f32_e32 v228, v228
	v_rcp_f32_e32 v229, v229
	v_pk_add_f32 v[230:231], v[230:231], v[222:223]
	v_rcp_f32_e32 v230, v230
	v_rcp_f32_e32 v231, v231
	v_pk_mul_f32 v[118:119], v[118:119], v[224:225]
	v_pk_mul_f32 v[120:121], v[120:121], v[226:227]
	v_pk_mul_f32 v[114:115], v[114:115], v[228:229]
	v_pk_mul_f32 v[116:117], v[116:117], v[230:231]
	v_cvt_pk_bf16_f32 v236, v118, v119
	v_cvt_pk_bf16_f32 v237, v120, v121
	v_cvt_pk_bf16_f32 v238, v114, v115
	v_cvt_pk_bf16_f32 v239, v116, v117
	global_store_dwordx4 v252, v[236:239], s[96:97]
	s_add_u32 s96, s96, 0x1000
	s_addc_u32 s97, s97, 0
	v_pk_mul_f32 v[224:225], v[110:111], v[220:221]
	v_pk_mul_f32 v[226:227], v[112:113], v[220:221]
	v_pk_mul_f32 v[228:229], v[106:107], v[220:221]
	v_pk_mul_f32 v[230:231], v[108:109], v[220:221]
	v_exp_f32_e32 v224, v224
	v_exp_f32_e32 v225, v225
	v_exp_f32_e32 v226, v226
	v_exp_f32_e32 v227, v227
	v_exp_f32_e32 v228, v228
	v_exp_f32_e32 v229, v229
	v_exp_f32_e32 v230, v230
	v_exp_f32_e32 v231, v231
	v_pk_add_f32 v[224:225], v[224:225], v[222:223]
	v_rcp_f32_e32 v224, v224
	v_rcp_f32_e32 v225, v225
	v_pk_add_f32 v[226:227], v[226:227], v[222:223]
	v_rcp_f32_e32 v226, v226
	v_rcp_f32_e32 v227, v227
	v_pk_add_f32 v[228:229], v[228:229], v[222:223]
	v_rcp_f32_e32 v228, v228
	v_rcp_f32_e32 v229, v229
	v_pk_add_f32 v[230:231], v[230:231], v[222:223]
	v_rcp_f32_e32 v230, v230
	v_rcp_f32_e32 v231, v231
	v_pk_mul_f32 v[110:111], v[110:111], v[224:225]
	v_pk_mul_f32 v[112:113], v[112:113], v[226:227]
	v_pk_mul_f32 v[106:107], v[106:107], v[228:229]
	v_pk_mul_f32 v[108:109], v[108:109], v[230:231]
	v_cvt_pk_bf16_f32 v232, v110, v111
	v_cvt_pk_bf16_f32 v233, v112, v113
	v_cvt_pk_bf16_f32 v234, v106, v107
	v_cvt_pk_bf16_f32 v235, v108, v109
	global_store_dwordx4 v252, v[232:235], s[96:97]
	s_add_u32 s96, s96, 0x1000
	s_addc_u32 s97, s97, 0
	v_pk_mul_f32 v[224:225], v[102:103], v[220:221]
	v_pk_mul_f32 v[226:227], v[104:105], v[220:221]
	v_pk_mul_f32 v[228:229], v[98:99], v[220:221]
	v_pk_mul_f32 v[230:231], v[100:101], v[220:221]
	v_exp_f32_e32 v224, v224
	v_exp_f32_e32 v225, v225
	v_exp_f32_e32 v226, v226
	v_exp_f32_e32 v227, v227
	v_exp_f32_e32 v228, v228
	v_exp_f32_e32 v229, v229
	v_exp_f32_e32 v230, v230
	v_exp_f32_e32 v231, v231
	v_pk_add_f32 v[224:225], v[224:225], v[222:223]
	v_rcp_f32_e32 v224, v224
	v_rcp_f32_e32 v225, v225
	v_pk_add_f32 v[226:227], v[226:227], v[222:223]
	v_rcp_f32_e32 v226, v226
	v_rcp_f32_e32 v227, v227
	v_pk_add_f32 v[228:229], v[228:229], v[222:223]
	v_rcp_f32_e32 v228, v228
	v_rcp_f32_e32 v229, v229
	v_pk_add_f32 v[230:231], v[230:231], v[222:223]
	v_rcp_f32_e32 v230, v230
	v_rcp_f32_e32 v231, v231
	v_pk_mul_f32 v[102:103], v[102:103], v[224:225]
	v_pk_mul_f32 v[104:105], v[104:105], v[226:227]
	v_pk_mul_f32 v[98:99], v[98:99], v[228:229]
	v_pk_mul_f32 v[100:101], v[100:101], v[230:231]
	v_cvt_pk_bf16_f32 v236, v102, v103
	v_cvt_pk_bf16_f32 v237, v104, v105
	v_cvt_pk_bf16_f32 v238, v98, v99
	v_cvt_pk_bf16_f32 v239, v100, v101
	global_store_dwordx4 v252, v[236:239], s[96:97]
	s_add_u32 s96, s96, 0x1000
	s_addc_u32 s97, s97, 0
	v_pk_mul_f32 v[224:225], v[94:95], v[220:221]
	v_pk_mul_f32 v[226:227], v[96:97], v[220:221]
	v_pk_mul_f32 v[228:229], v[90:91], v[220:221]
	v_pk_mul_f32 v[230:231], v[92:93], v[220:221]
	v_exp_f32_e32 v224, v224
	v_exp_f32_e32 v225, v225
	v_exp_f32_e32 v226, v226
	v_exp_f32_e32 v227, v227
	v_exp_f32_e32 v228, v228
	v_exp_f32_e32 v229, v229
	v_exp_f32_e32 v230, v230
	v_exp_f32_e32 v231, v231
	v_pk_add_f32 v[224:225], v[224:225], v[222:223]
	v_rcp_f32_e32 v224, v224
	v_rcp_f32_e32 v225, v225
	v_pk_add_f32 v[226:227], v[226:227], v[222:223]
; __device__ __forceinline__ unsigned cvt_pk_bf16(float lo, float hi) { unsigned r; asm volatile("v_cvt_pk_bf16_f32 %0, %1, %2" : "=v"(r) : "v"(lo), "v"(hi)); return r; }
; __device__ __forceinline__ float silu_f(float x) { return x * __builtin_amdgcn_rcpf(1.0f + __builtin_amdgcn_exp2f(-x * LOG2E)); }
;     __device__ __forceinline__ void operator()(const f32x4 (&acc)[2][2][4][2], const pg8::Unit& u, int wr, int wc, int fr, int fq, const LAS float* tab) const {
;     ...
;         for (int ai = 0; ai < 2; ++ai)
; #pragma unroll
;             for (int m = 0; m < 4; ++m) {
;                 const int row = row0 + ai * 128 + m * 16;
;                 bf16_t* rowp = (mode == 0) ? base + (size_t)(row >> 4) * 4096 + (size_t)(wc * 512 + (row & 15) * 32 + 8 * fq) : base + (size_t)row * ldc + col0;
;                 const int bjstep = (mode == 0) ? 4 * 512 : 128;
;                 float s1 = 0.f, s2 = 0.f;
;                 const float f2 = (kind == 4) ? tab[512 + ai * 128 + wr * 64 + m * 16 + fr] : 1.0f;
; #pragma unroll
;                 for (int bj = 0; bj < 2; ++bj) {
;                     f32x4 v0 = acc[ai][bj][m][0], v1 = acc[ai][bj][m][1];
;                     if (kind == 1) {
; #pragma unroll
;                         for (int e = 0; e < 4; ++e) { v0[e] = silu_f(v0[e]); v1[e] = silu_f(v1[e]); }
;                     } else if (kind == 2) { v0 = v0 * QSCALE; v1 = v1 * QSCALE; }
;                     else if (kind == 3) {
; #pragma unroll
;                         for (int e = 0; e < 4; ++e) { s1 += v0[e] + v1[e]; s2 += v0[e] * v0[e] + v1[e] * v1[e]; }
;                     } else if (kind == 4) {
;                         v0 = v0 * f2; v1 = v1 * f2;
; #pragma unroll
;                         for (int e = 0; e < 4; ++e) s2 += v0[e] * v0[e] + v1[e] * v1[e];
;                     }
;                     u32x4 w; w.x = cvt_pk_bf16(v0[0], v0[1]); w.y = cvt_pk_bf16(v0[2], v0[3]); w.z = cvt_pk_bf16(v1[0], v1[1]); w.w = cvt_pk_bf16(v1[2], v1[3]);
;                     *(u32x4*)(rowp + bj * bjstep) = w;
	v_rcp_f32_e32 v226, v226
	v_rcp_f32_e32 v227, v227
	v_pk_add_f32 v[228:229], v[228:229], v[222:223]
	v_rcp_f32_e32 v228, v228
	v_rcp_f32_e32 v229, v229
	v_pk_add_f32 v[230:231], v[230:231], v[222:223]
	v_rcp_f32_e32 v230, v230
	v_rcp_f32_e32 v231, v231
	v_pk_mul_f32 v[94:95], v[94:95], v[224:225]
	v_pk_mul_f32 v[96:97], v[96:97], v[226:227]
	v_pk_mul_f32 v[90:91], v[90:91], v[228:229]
	v_pk_mul_f32 v[92:93], v[92:93], v[230:231]
	v_cvt_pk_bf16_f32 v232, v94, v95
	v_cvt_pk_bf16_f32 v233, v96, v97
	v_cvt_pk_bf16_f32 v234, v90, v91
	v_cvt_pk_bf16_f32 v235, v92, v93
	global_store_dwordx4 v252, v[232:235], s[96:97]
	s_add_u32 s96, s96, 0x1000
	s_addc_u32 s97, s97, 0
	v_pk_mul_f32 v[224:225], v[86:87], v[220:221]
	v_pk_mul_f32 v[226:227], v[88:89], v[220:221]
	v_pk_mul_f32 v[228:229], v[82:83], v[220:221]
	v_pk_mul_f32 v[230:231], v[84:85], v[220:221]
	v_exp_f32_e32 v224, v224
	v_exp_f32_e32 v225, v225
	v_exp_f32_e32 v226, v226
	v_exp_f32_e32 v227, v227
	v_exp_f32_e32 v228, v228
	v_exp_f32_e32 v229, v229
	v_exp_f32_e32 v230, v230
	v_exp_f32_e32 v231, v231
	v_pk_add_f32 v[224:225], v[224:225], v[222:223]
	v_rcp_f32_e32 v224, v224
	v_rcp_f32_e32 v225, v225
	v_pk_add_f32 v[226:227], v[226:227], v[222:223]
	v_rcp_f32_e32 v226, v226
	v_rcp_f32_e32 v227, v227
	v_pk_add_f32 v[228:229], v[228:229], v[222:223]
	v_rcp_f32_e32 v228, v228
	v_rcp_f32_e32 v229, v229
	v_pk_add_f32 v[230:231], v[230:231], v[222:223]
	v_rcp_f32_e32 v230, v230
	v_rcp_f32_e32 v231, v231
	v_pk_mul_f32 v[86:87], v[86:87], v[224:225]
	v_pk_mul_f32 v[88:89], v[88:89], v[226:227]
	v_pk_mul_f32 v[82:83], v[82:83], v[228:229]
	v_pk_mul_f32 v[84:85], v[84:85], v[230:231]
	v_cvt_pk_bf16_f32 v236, v86, v87
	v_cvt_pk_bf16_f32 v237, v88, v89
	v_cvt_pk_bf16_f32 v238, v82, v83
	v_cvt_pk_bf16_f32 v239, v84, v85
	global_store_dwordx4 v252, v[236:239], s[96:97]
	s_add_u32 s96, s96, 0x1000
	s_addc_u32 s97, s97, 0
	v_pk_mul_f32 v[224:225], v[78:79], v[220:221]
	v_pk_mul_f32 v[226:227], v[80:81], v[220:221]
	v_pk_mul_f32 v[228:229], v[74:75], v[220:221]
	v_pk_mul_f32 v[230:231], v[76:77], v[220:221]
	v_exp_f32_e32 v224, v224
	v_exp_f32_e32 v225, v225
	v_exp_f32_e32 v226, v226
	v_exp_f32_e32 v227, v227
	v_exp_f32_e32 v228, v228
	v_exp_f32_e32 v229, v229
	v_exp_f32_e32 v230, v230
	v_exp_f32_e32 v231, v231
	v_pk_add_f32 v[224:225], v[224:225], v[222:223]
	v_rcp_f32_e32 v224, v224
	v_rcp_f32_e32 v225, v225
	v_pk_add_f32 v[226:227], v[226:227], v[222:223]
	v_rcp_f32_e32 v226, v226
	v_rcp_f32_e32 v227, v227
	v_pk_add_f32 v[228:229], v[228:229], v[222:223]
	v_rcp_f32_e32 v228, v228
	v_rcp_f32_e32 v229, v229
	v_pk_add_f32 v[230:231], v[230:231], v[222:223]
	v_rcp_f32_e32 v230, v230
	v_rcp_f32_e32 v231, v231
	v_pk_mul_f32 v[78:79], v[78:79], v[224:225]
	v_pk_mul_f32 v[80:81], v[80:81], v[226:227]
	v_pk_mul_f32 v[74:75], v[74:75], v[228:229]
	v_pk_mul_f32 v[76:77], v[76:77], v[230:231]
	v_cvt_pk_bf16_f32 v232, v78, v79
	v_cvt_pk_bf16_f32 v233, v80, v81
	v_cvt_pk_bf16_f32 v234, v74, v75
	v_cvt_pk_bf16_f32 v235, v76, v77
	global_store_dwordx4 v252, v[232:235], s[96:97]
	s_add_u32 s96, s96, 0x1000
	s_addc_u32 s97, s97, 0
	v_pk_mul_f32 v[224:225], v[70:71], v[220:221]
	v_pk_mul_f32 v[226:227], v[72:73], v[220:221]
	v_pk_mul_f32 v[228:229], v[66:67], v[220:221]
	v_pk_mul_f32 v[230:231], v[68:69], v[220:221]
	v_exp_f32_e32 v224, v224
	v_exp_f32_e32 v225, v225
	v_exp_f32_e32 v226, v226
	v_exp_f32_e32 v227, v227
	v_exp_f32_e32 v228, v228
	v_exp_f32_e32 v229, v229
	v_exp_f32_e32 v230, v230
	v_exp_f32_e32 v231, v231
	v_pk_add_f32 v[224:225], v[224:225], v[222:223]
	v_rcp_f32_e32 v224, v224
	v_rcp_f32_e32 v225, v225
	v_pk_add_f32 v[226:227], v[226:227], v[222:223]
	v_rcp_f32_e32 v226, v226
	v_rcp_f32_e32 v227, v227
	v_pk_add_f32 v[228:229], v[228:229], v[222:223]
	v_rcp_f32_e32 v228, v228
	v_rcp_f32_e32 v229, v229
	v_pk_add_f32 v[230:231], v[230:231], v[222:223]
	v_rcp_f32_e32 v230, v230
	v_rcp_f32_e32 v231, v231
	v_pk_mul_f32 v[70:71], v[70:71], v[224:225]
	v_pk_mul_f32 v[72:73], v[72:73], v[226:227]
	v_pk_mul_f32 v[66:67], v[66:67], v[228:229]
	v_pk_mul_f32 v[68:69], v[68:69], v[230:231]
	v_cvt_pk_bf16_f32 v236, v70, v71
	v_cvt_pk_bf16_f32 v237, v72, v73
	v_cvt_pk_bf16_f32 v238, v66, v67
	v_cvt_pk_bf16_f32 v239, v68, v69
	global_store_dwordx4 v252, v[236:239], s[96:97]
	s_add_u32 s96, s96, 0x1000
	s_addc_u32 s97, s97, 0
	s_add_u32 s96, s96, 0x8000
	s_addc_u32 s97, s97, 0
	v_pk_mul_f32 v[224:225], v[62:63], v[220:221]
	v_pk_mul_f32 v[226:227], v[64:65], v[220:221]
	v_pk_mul_f32 v[228:229], v[58:59], v[220:221]
	v_pk_mul_f32 v[230:231], v[60:61], v[220:221]
	v_exp_f32_e32 v224, v224
	v_exp_f32_e32 v225, v225
	v_exp_f32_e32 v226, v226
	v_exp_f32_e32 v227, v227
	v_exp_f32_e32 v228, v228
	v_exp_f32_e32 v229, v229
	v_exp_f32_e32 v230, v230
	v_exp_f32_e32 v231, v231
	v_pk_add_f32 v[224:225], v[224:225], v[222:223]
	v_rcp_f32_e32 v224, v224
	v_rcp_f32_e32 v225, v225
	v_pk_add_f32 v[226:227], v[226:227], v[222:223]
	v_rcp_f32_e32 v226, v226
	v_rcp_f32_e32 v227, v227
	v_pk_add_f32 v[228:229], v[228:229], v[222:223]
	v_rcp_f32_e32 v228, v228
	v_rcp_f32_e32 v229, v229
	v_pk_add_f32 v[230:231], v[230:231], v[222:223]
	v_rcp_f32_e32 v230, v230
	v_rcp_f32_e32 v231, v231
	v_pk_mul_f32 v[62:63], v[62:63], v[224:225]
	v_pk_mul_f32 v[64:65], v[64:65], v[226:227]
	v_pk_mul_f32 v[58:59], v[58:59], v[228:229]
	v_pk_mul_f32 v[60:61], v[60:61], v[230:231]
	v_cvt_pk_bf16_f32 v232, v62, v63
	v_cvt_pk_bf16_f32 v233, v64, v65
	v_cvt_pk_bf16_f32 v234, v58, v59
	v_cvt_pk_bf16_f32 v235, v60, v61
	global_store_dwordx4 v252, v[232:235], s[96:97]
	s_add_u32 s96, s96, 0x1000
	s_addc_u32 s97, s97, 0
	v_pk_mul_f32 v[224:225], v[54:55], v[220:221]
; __device__ __forceinline__ unsigned cvt_pk_bf16(float lo, float hi) { unsigned r; asm volatile("v_cvt_pk_bf16_f32 %0, %1, %2" : "=v"(r) : "v"(lo), "v"(hi)); return r; }
; __device__ __forceinline__ float silu_f(float x) { return x * __builtin_amdgcn_rcpf(1.0f + __builtin_amdgcn_exp2f(-x * LOG2E)); }
;     __device__ __forceinline__ void operator()(const f32x4 (&acc)[2][2][4][2], const pg8::Unit& u, int wr, int wc, int fr, int fq, const LAS float* tab) const {
;     ...
;         for (int ai = 0; ai < 2; ++ai)
; #pragma unroll
;             for (int m = 0; m < 4; ++m) {
;                 const int row = row0 + ai * 128 + m * 16;
;                 bf16_t* rowp = (mode == 0) ? base + (size_t)(row >> 4) * 4096 + (size_t)(wc * 512 + (row & 15) * 32 + 8 * fq) : base + (size_t)row * ldc + col0;
;                 const int bjstep = (mode == 0) ? 4 * 512 : 128;
;                 float s1 = 0.f, s2 = 0.f;
;                 const float f2 = (kind == 4) ? tab[512 + ai * 128 + wr * 64 + m * 16 + fr] : 1.0f;
; #pragma unroll
;                 for (int bj = 0; bj < 2; ++bj) {
;                     f32x4 v0 = acc[ai][bj][m][0], v1 = acc[ai][bj][m][1];
;                     if (kind == 1) {
; #pragma unroll
;                         for (int e = 0; e < 4; ++e) { v0[e] = silu_f(v0[e]); v1[e] = silu_f(v1[e]); }
;                     } else if (kind == 2) { v0 = v0 * QSCALE; v1 = v1 * QSCALE; }
;                     else if (kind == 3) {
; #pragma unroll
;                         for (int e = 0; e < 4; ++e) { s1 += v0[e] + v1[e]; s2 += v0[e] * v0[e] + v1[e] * v1[e]; }
;                     } else if (kind == 4) {
;                         v0 = v0 * f2; v1 = v1 * f2;
; #pragma unroll
;                         for (int e = 0; e < 4; ++e) s2 += v0[e] * v0[e] + v1[e] * v1[e];
;                     }
;                     u32x4 w; w.x = cvt_pk_bf16(v0[0], v0[1]); w.y = cvt_pk_bf16(v0[2], v0[3]); w.z = cvt_pk_bf16(v1[0], v1[1]); w.w = cvt_pk_bf16(v1[2], v1[3]);
;                     *(u32x4*)(rowp + bj * bjstep) = w;
	v_pk_mul_f32 v[226:227], v[56:57], v[220:221]
	v_pk_mul_f32 v[228:229], v[50:51], v[220:221]
	v_pk_mul_f32 v[230:231], v[52:53], v[220:221]
	v_exp_f32_e32 v224, v224
	v_exp_f32_e32 v225, v225
	v_exp_f32_e32 v226, v226
	v_exp_f32_e32 v227, v227
	v_exp_f32_e32 v228, v228
	v_exp_f32_e32 v229, v229
	v_exp_f32_e32 v230, v230
	v_exp_f32_e32 v231, v231
	v_pk_add_f32 v[224:225], v[224:225], v[222:223]
	v_rcp_f32_e32 v224, v224
	v_rcp_f32_e32 v225, v225
	v_pk_add_f32 v[226:227], v[226:227], v[222:223]
	v_rcp_f32_e32 v226, v226
	v_rcp_f32_e32 v227, v227
	v_pk_add_f32 v[228:229], v[228:229], v[222:223]
	v_rcp_f32_e32 v228, v228
	v_rcp_f32_e32 v229, v229
	v_pk_add_f32 v[230:231], v[230:231], v[222:223]
	v_rcp_f32_e32 v230, v230
	v_rcp_f32_e32 v231, v231
	v_pk_mul_f32 v[54:55], v[54:55], v[224:225]
	v_pk_mul_f32 v[56:57], v[56:57], v[226:227]
	v_pk_mul_f32 v[50:51], v[50:51], v[228:229]
	v_pk_mul_f32 v[52:53], v[52:53], v[230:231]
	v_cvt_pk_bf16_f32 v236, v54, v55
	v_cvt_pk_bf16_f32 v237, v56, v57
	v_cvt_pk_bf16_f32 v238, v50, v51
	v_cvt_pk_bf16_f32 v239, v52, v53
	global_store_dwordx4 v252, v[236:239], s[96:97]
	s_add_u32 s96, s96, 0x1000
	s_addc_u32 s97, s97, 0
	v_pk_mul_f32 v[224:225], v[46:47], v[220:221]
	v_pk_mul_f32 v[226:227], v[48:49], v[220:221]
	v_pk_mul_f32 v[228:229], v[42:43], v[220:221]
	v_pk_mul_f32 v[230:231], v[44:45], v[220:221]
	v_exp_f32_e32 v224, v224
	v_exp_f32_e32 v225, v225
	v_exp_f32_e32 v226, v226
	v_exp_f32_e32 v227, v227
	v_exp_f32_e32 v228, v228
	v_exp_f32_e32 v229, v229
	v_exp_f32_e32 v230, v230
	v_exp_f32_e32 v231, v231
	v_pk_add_f32 v[224:225], v[224:225], v[222:223]
	v_rcp_f32_e32 v224, v224
	v_rcp_f32_e32 v225, v225
	v_pk_add_f32 v[226:227], v[226:227], v[222:223]
	v_rcp_f32_e32 v226, v226
	v_rcp_f32_e32 v227, v227
	v_pk_add_f32 v[228:229], v[228:229], v[222:223]
	v_rcp_f32_e32 v228, v228
	v_rcp_f32_e32 v229, v229
	v_pk_add_f32 v[230:231], v[230:231], v[222:223]
	v_rcp_f32_e32 v230, v230
	v_rcp_f32_e32 v231, v231
	v_pk_mul_f32 v[46:47], v[46:47], v[224:225]
	v_pk_mul_f32 v[48:49], v[48:49], v[226:227]
	v_pk_mul_f32 v[42:43], v[42:43], v[228:229]
	v_pk_mul_f32 v[44:45], v[44:45], v[230:231]
	v_cvt_pk_bf16_f32 v232, v46, v47
	v_cvt_pk_bf16_f32 v233, v48, v49
	v_cvt_pk_bf16_f32 v234, v42, v43
	v_cvt_pk_bf16_f32 v235, v44, v45
	global_store_dwordx4 v252, v[232:235], s[96:97]
	s_add_u32 s96, s96, 0x1000
	s_addc_u32 s97, s97, 0
	v_pk_mul_f32 v[224:225], v[38:39], v[220:221]
	v_pk_mul_f32 v[226:227], v[40:41], v[220:221]
	v_pk_mul_f32 v[228:229], v[34:35], v[220:221]
	v_pk_mul_f32 v[230:231], v[36:37], v[220:221]
	v_exp_f32_e32 v224, v224
	v_exp_f32_e32 v225, v225
	v_exp_f32_e32 v226, v226
	v_exp_f32_e32 v227, v227
	v_exp_f32_e32 v228, v228
	v_exp_f32_e32 v229, v229
	v_exp_f32_e32 v230, v230
	v_exp_f32_e32 v231, v231
	v_pk_add_f32 v[224:225], v[224:225], v[222:223]
	v_rcp_f32_e32 v224, v224
	v_rcp_f32_e32 v225, v225
	v_pk_add_f32 v[226:227], v[226:227], v[222:223]
	v_rcp_f32_e32 v226, v226
	v_rcp_f32_e32 v227, v227
	v_pk_add_f32 v[228:229], v[228:229], v[222:223]
	v_rcp_f32_e32 v228, v228
	v_rcp_f32_e32 v229, v229
	v_pk_add_f32 v[230:231], v[230:231], v[222:223]
	v_rcp_f32_e32 v230, v230
	v_rcp_f32_e32 v231, v231
	v_pk_mul_f32 v[38:39], v[38:39], v[224:225]
	v_pk_mul_f32 v[40:41], v[40:41], v[226:227]
	v_pk_mul_f32 v[34:35], v[34:35], v[228:229]
	v_pk_mul_f32 v[36:37], v[36:37], v[230:231]
	v_cvt_pk_bf16_f32 v236, v38, v39
	v_cvt_pk_bf16_f32 v237, v40, v41
	v_cvt_pk_bf16_f32 v238, v34, v35
	v_cvt_pk_bf16_f32 v239, v36, v37
	global_store_dwordx4 v252, v[236:239], s[96:97]
	s_add_u32 s96, s96, 0x1000
	s_addc_u32 s97, s97, 0
	v_pk_mul_f32 v[224:225], v[30:31], v[220:221]
	v_pk_mul_f32 v[226:227], v[32:33], v[220:221]
	v_pk_mul_f32 v[228:229], v[26:27], v[220:221]
	v_pk_mul_f32 v[230:231], v[28:29], v[220:221]
	v_exp_f32_e32 v224, v224
	v_exp_f32_e32 v225, v225
	v_exp_f32_e32 v226, v226
	v_exp_f32_e32 v227, v227
	v_exp_f32_e32 v228, v228
	v_exp_f32_e32 v229, v229
	v_exp_f32_e32 v230, v230
	v_exp_f32_e32 v231, v231
	v_pk_add_f32 v[224:225], v[224:225], v[222:223]
	v_rcp_f32_e32 v224, v224
	v_rcp_f32_e32 v225, v225
	v_pk_add_f32 v[226:227], v[226:227], v[222:223]
	v_rcp_f32_e32 v226, v226
	v_rcp_f32_e32 v227, v227
	v_pk_add_f32 v[228:229], v[228:229], v[222:223]
; __device__ __forceinline__ unsigned cvt_pk_bf16(float lo, float hi) { unsigned r; asm volatile("v_cvt_pk_bf16_f32 %0, %1, %2" : "=v"(r) : "v"(lo), "v"(hi)); return r; }
; __device__ __forceinline__ float silu_f(float x) { return x * __builtin_amdgcn_rcpf(1.0f + __builtin_amdgcn_exp2f(-x * LOG2E)); }
;     __device__ __forceinline__ void operator()(const f32x4 (&acc)[2][2][4][2], const pg8::Unit& u, int wr, int wc, int fr, int fq, const LAS float* tab) const {
;     ...
;         for (int ai = 0; ai < 2; ++ai)
; #pragma unroll
;             for (int m = 0; m < 4; ++m) {
;                 const int row = row0 + ai * 128 + m * 16;
;                 bf16_t* rowp = (mode == 0) ? base + (size_t)(row >> 4) * 4096 + (size_t)(wc * 512 + (row & 15) * 32 + 8 * fq) : base + (size_t)row * ldc + col0;
;                 const int bjstep = (mode == 0) ? 4 * 512 : 128;
;                 float s1 = 0.f, s2 = 0.f;
;                 const float f2 = (kind == 4) ? tab[512 + ai * 128 + wr * 64 + m * 16 + fr] : 1.0f;
; #pragma unroll
;                 for (int bj = 0; bj < 2; ++bj) {
;                     f32x4 v0 = acc[ai][bj][m][0], v1 = acc[ai][bj][m][1];
;                     if (kind == 1) {
; #pragma unroll
;                         for (int e = 0; e < 4; ++e) { v0[e] = silu_f(v0[e]); v1[e] = silu_f(v1[e]); }
;                     } else if (kind == 2) { v0 = v0 * QSCALE; v1 = v1 * QSCALE; }
;                     else if (kind == 3) {
; #pragma unroll
;                         for (int e = 0; e < 4; ++e) { s1 += v0[e] + v1[e]; s2 += v0[e] * v0[e] + v1[e] * v1[e]; }
;                     } else if (kind == 4) {
;                         v0 = v0 * f2; v1 = v1 * f2;
; #pragma unroll
;                         for (int e = 0; e < 4; ++e) s2 += v0[e] * v0[e] + v1[e] * v1[e];
;                     }
;                     u32x4 w; w.x = cvt_pk_bf16(v0[0], v0[1]); w.y = cvt_pk_bf16(v0[2], v0[3]); w.z = cvt_pk_bf16(v1[0], v1[1]); w.w = cvt_pk_bf16(v1[2], v1[3]);
;                     *(u32x4*)(rowp + bj * bjstep) = w;
	v_rcp_f32_e32 v228, v228
	v_rcp_f32_e32 v229, v229
	v_pk_add_f32 v[230:231], v[230:231], v[222:223]
	v_rcp_f32_e32 v230, v230
	v_rcp_f32_e32 v231, v231
	v_pk_mul_f32 v[30:31], v[30:31], v[224:225]
	v_pk_mul_f32 v[32:33], v[32:33], v[226:227]
	v_pk_mul_f32 v[26:27], v[26:27], v[228:229]
	v_pk_mul_f32 v[28:29], v[28:29], v[230:231]
	v_cvt_pk_bf16_f32 v232, v30, v31
	v_cvt_pk_bf16_f32 v233, v32, v33
	v_cvt_pk_bf16_f32 v234, v26, v27
	v_cvt_pk_bf16_f32 v235, v28, v29
	global_store_dwordx4 v252, v[232:235], s[96:97]
	s_add_u32 s96, s96, 0x1000
	s_addc_u32 s97, s97, 0
	v_pk_mul_f32 v[224:225], v[22:23], v[220:221]
	v_pk_mul_f32 v[226:227], v[24:25], v[220:221]
	v_pk_mul_f32 v[228:229], v[18:19], v[220:221]
	v_pk_mul_f32 v[230:231], v[20:21], v[220:221]
	v_exp_f32_e32 v224, v224
	v_exp_f32_e32 v225, v225
	v_exp_f32_e32 v226, v226
	v_exp_f32_e32 v227, v227
	v_exp_f32_e32 v228, v228
	v_exp_f32_e32 v229, v229
	v_exp_f32_e32 v230, v230
	v_exp_f32_e32 v231, v231
	v_pk_add_f32 v[224:225], v[224:225], v[222:223]
	v_rcp_f32_e32 v224, v224
	v_rcp_f32_e32 v225, v225
	v_pk_add_f32 v[226:227], v[226:227], v[222:223]
	v_rcp_f32_e32 v226, v226
	v_rcp_f32_e32 v227, v227
	v_pk_add_f32 v[228:229], v[228:229], v[222:223]
	v_rcp_f32_e32 v228, v228
	v_rcp_f32_e32 v229, v229
	v_pk_add_f32 v[230:231], v[230:231], v[222:223]
	v_rcp_f32_e32 v230, v230
	v_rcp_f32_e32 v231, v231
	v_pk_mul_f32 v[22:23], v[22:23], v[224:225]
	v_pk_mul_f32 v[24:25], v[24:25], v[226:227]
	v_pk_mul_f32 v[18:19], v[18:19], v[228:229]
	v_pk_mul_f32 v[20:21], v[20:21], v[230:231]
	v_cvt_pk_bf16_f32 v236, v22, v23
	v_cvt_pk_bf16_f32 v237, v24, v25
	v_cvt_pk_bf16_f32 v238, v18, v19
	v_cvt_pk_bf16_f32 v239, v20, v21
	global_store_dwordx4 v252, v[236:239], s[96:97]
	s_add_u32 s96, s96, 0x1000
	s_addc_u32 s97, s97, 0
	v_pk_mul_f32 v[224:225], v[14:15], v[220:221]
	v_pk_mul_f32 v[226:227], v[16:17], v[220:221]
	v_pk_mul_f32 v[228:229], v[10:11], v[220:221]
	v_pk_mul_f32 v[230:231], v[12:13], v[220:221]
	v_exp_f32_e32 v224, v224
	v_exp_f32_e32 v225, v225
	v_exp_f32_e32 v226, v226
	v_exp_f32_e32 v227, v227
	v_exp_f32_e32 v228, v228
	v_exp_f32_e32 v229, v229
	v_exp_f32_e32 v230, v230
	v_exp_f32_e32 v231, v231
	v_pk_add_f32 v[224:225], v[224:225], v[222:223]
	v_rcp_f32_e32 v224, v224
	v_rcp_f32_e32 v225, v225
	v_pk_add_f32 v[226:227], v[226:227], v[222:223]
	v_rcp_f32_e32 v226, v226
	v_rcp_f32_e32 v227, v227
	v_pk_add_f32 v[228:229], v[228:229], v[222:223]
	v_rcp_f32_e32 v228, v228
	v_rcp_f32_e32 v229, v229
	v_pk_add_f32 v[230:231], v[230:231], v[222:223]
	v_rcp_f32_e32 v230, v230
	v_rcp_f32_e32 v231, v231
	v_pk_mul_f32 v[14:15], v[14:15], v[224:225]
	v_pk_mul_f32 v[16:17], v[16:17], v[226:227]
	v_pk_mul_f32 v[10:11], v[10:11], v[228:229]
	v_pk_mul_f32 v[12:13], v[12:13], v[230:231]
	v_cvt_pk_bf16_f32 v232, v14, v15
	v_cvt_pk_bf16_f32 v233, v16, v17
	v_cvt_pk_bf16_f32 v234, v10, v11
	v_cvt_pk_bf16_f32 v235, v12, v13
	global_store_dwordx4 v252, v[232:235], s[96:97]
	s_add_u32 s96, s96, 0x1000
	s_addc_u32 s97, s97, 0
	v_pk_mul_f32 v[224:225], v[6:7], v[220:221]
	v_pk_mul_f32 v[226:227], v[8:9], v[220:221]
	v_pk_mul_f32 v[228:229], v[2:3], v[220:221]
	v_pk_mul_f32 v[230:231], v[4:5], v[220:221]
	v_exp_f32_e32 v224, v224
	v_exp_f32_e32 v225, v225
	v_exp_f32_e32 v226, v226
	v_exp_f32_e32 v227, v227
	v_exp_f32_e32 v228, v228
	v_exp_f32_e32 v229, v229
	v_exp_f32_e32 v230, v230
	v_exp_f32_e32 v231, v231
	v_pk_add_f32 v[224:225], v[224:225], v[222:223]
	v_rcp_f32_e32 v224, v224
	v_rcp_f32_e32 v225, v225
	v_pk_add_f32 v[226:227], v[226:227], v[222:223]
	v_rcp_f32_e32 v226, v226
	v_rcp_f32_e32 v227, v227
	v_pk_add_f32 v[228:229], v[228:229], v[222:223]
	v_rcp_f32_e32 v228, v228
	v_rcp_f32_e32 v229, v229
	v_pk_add_f32 v[230:231], v[230:231], v[222:223]
	v_rcp_f32_e32 v230, v230
	v_rcp_f32_e32 v231, v231
	v_pk_mul_f32 v[6:7], v[6:7], v[224:225]
	v_pk_mul_f32 v[8:9], v[8:9], v[226:227]
	v_pk_mul_f32 v[2:3], v[2:3], v[228:229]
	v_pk_mul_f32 v[4:5], v[4:5], v[230:231]
	v_cvt_pk_bf16_f32 v236, v6, v7
	v_cvt_pk_bf16_f32 v237, v8, v9
	v_cvt_pk_bf16_f32 v238, v2, v3
	v_cvt_pk_bf16_f32 v239, v4, v5
	global_store_dwordx4 v252, v[236:239], s[96:97]
	s_add_u32 s96, s96, 0x1000
	s_addc_u32 s97, s97, 0
	s_branch .LBB0_391
